# v29
# speedup vs baseline: 1.0288x; 1.0049x over previous
.LBB0_219:
	ds_read_b128 v[164:167], v160
	ds_read_b128 v[168:171], v160 offset:1024
	ds_read_b128 v[172:175], v160 offset:2048
	ds_read_b128 v[176:179], v160 offset:3072
	v_lshl_add_u64 v[240:241], v[144:145], 0, s[6:7]
	s_add_i32 m0, s100, 0xbf80
	ds_read_b128 v[184:187], v152
	ds_read_b128 v[190:193], v152 offset:1024
	ds_read_b128 v[194:197], v151
	ds_read_b128 v[198:201], v151 offset:1024
	ds_read_b128 v[206:209], v150
	ds_read_b128 v[212:215], v150 offset:1024
	ds_read_b128 v[216:219], v149
	ds_read_b128 v[220:223], v149 offset:1024
	global_load_lds_dwordx4 v[240:241], off offset:128
	s_add_i32 m0, s100, 0xdf80
	v_lshl_add_u64 v[242:243], v[142:143], 0, s[6:7]
	global_load_lds_dwordx4 v[242:243], off offset:128
	s_waitcnt lgkmcnt(8)
	s_barrier
	s_waitcnt lgkmcnt(0)
	v_mfma_f32_16x16x32_bf16 v[124:127], v[184:187], v[164:167], v[124:127]
	v_mfma_f32_16x16x32_bf16 v[120:123], v[184:187], v[172:175], v[120:123]
	v_mfma_f32_16x16x32_bf16 v[116:119], v[194:197], v[164:167], v[116:119]
	v_mfma_f32_16x16x32_bf16 v[112:115], v[194:197], v[172:175], v[112:115]
	v_mfma_f32_16x16x32_bf16 v[108:111], v[206:209], v[164:167], v[108:111]
	v_mfma_f32_16x16x32_bf16 v[104:107], v[206:209], v[172:175], v[104:107]
	v_mfma_f32_16x16x32_bf16 v[100:103], v[216:219], v[164:167], v[100:103]
	v_mfma_f32_16x16x32_bf16 v[96:99], v[216:219], v[172:175], v[96:99]
	v_mfma_f32_16x16x32_bf16 v[124:127], v[190:193], v[168:171], v[124:127]
	v_mfma_f32_16x16x32_bf16 v[120:123], v[190:193], v[176:179], v[120:123]
	v_mfma_f32_16x16x32_bf16 v[116:119], v[198:201], v[168:171], v[116:119]
	v_mfma_f32_16x16x32_bf16 v[112:115], v[198:201], v[176:179], v[112:115]
	v_mfma_f32_16x16x32_bf16 v[108:111], v[212:215], v[168:171], v[108:111]
	v_mfma_f32_16x16x32_bf16 v[104:107], v[212:215], v[176:179], v[104:107]
	v_mfma_f32_16x16x32_bf16 v[100:103], v[220:223], v[168:171], v[100:103]
	v_mfma_f32_16x16x32_bf16 v[96:99], v[220:223], v[176:179], v[96:99]
	s_barrier
	v_lshl_add_u64 v[244:245], v[130:131], 0, s[6:7]
	s_add_i32 m0, s101, 0xff00
	ds_read_b128 v[224:227], v159
	ds_read_b128 v[228:231], v159 offset:1024
	ds_read_b128 v[232:235], v159 offset:2048
	ds_read_b128 v[236:239], v159 offset:3072
	global_load_lds_dwordx4 v[244:245], off offset:256
	v_lshl_add_u64 v[246:247], v[132:133], 0, s[6:7]
	s_add_i32 m0, m0, 0x2000
	s_add_i32 s11, s11, 2
	global_load_lds_dwordx4 v[246:247], off offset:256
	s_barrier
	s_waitcnt lgkmcnt(0)
	v_mfma_f32_16x16x32_bf16 v[92:95], v[184:187], v[224:227], v[92:95]
	v_mfma_f32_16x16x32_bf16 v[88:91], v[184:187], v[232:235], v[88:91]
	v_mfma_f32_16x16x32_bf16 v[84:87], v[194:197], v[224:227], v[84:87]
	v_mfma_f32_16x16x32_bf16 v[80:83], v[194:197], v[232:235], v[80:83]
	v_mfma_f32_16x16x32_bf16 v[76:79], v[206:209], v[224:227], v[76:79]
	v_mfma_f32_16x16x32_bf16 v[72:75], v[206:209], v[232:235], v[72:75]
	v_mfma_f32_16x16x32_bf16 v[68:71], v[216:219], v[224:227], v[68:71]
	v_mfma_f32_16x16x32_bf16 v[64:67], v[216:219], v[232:235], v[64:67]
	v_mfma_f32_16x16x32_bf16 v[92:95], v[190:193], v[228:231], v[92:95]
	v_mfma_f32_16x16x32_bf16 v[88:91], v[190:193], v[236:239], v[88:91]
	v_mfma_f32_16x16x32_bf16 v[84:87], v[198:201], v[228:231], v[84:87]
	v_mfma_f32_16x16x32_bf16 v[80:83], v[198:201], v[236:239], v[80:83]
	v_mfma_f32_16x16x32_bf16 v[76:79], v[212:215], v[228:231], v[76:79]
	v_mfma_f32_16x16x32_bf16 v[72:75], v[212:215], v[236:239], v[72:75]
	v_mfma_f32_16x16x32_bf16 v[68:71], v[220:223], v[228:231], v[68:71]
	v_mfma_f32_16x16x32_bf16 v[64:67], v[220:223], v[236:239], v[64:67]
	v_lshl_add_u64 v[248:249], v[134:135], 0, s[6:7]
	v_lshl_add_u64 v[250:251], v[248:249], 0, s[64:65]
	s_mov_b32 m0, s100
	s_barrier
	ds_read_b128 v[184:187], v152 offset:16384
	ds_read_b128 v[190:193], v152 offset:17408
	ds_read_b128 v[194:197], v151 offset:16384
	ds_read_b128 v[198:201], v151 offset:17408
	ds_read_b128 v[206:209], v150 offset:16384
	ds_read_b128 v[212:215], v150 offset:17408
	ds_read_b128 v[216:219], v149 offset:16384
	ds_read_b128 v[220:223], v149 offset:17408
	global_load_lds_dwordx4 v[250:251], off
	s_add_i32 m0, s100, 0x1f00
	v_lshl_add_u64 v[250:251], v[136:137], 0, s[6:7]
	global_load_lds_dwordx4 v[250:251], off offset:256
	s_barrier
	s_waitcnt lgkmcnt(0)
	v_mfma_f32_16x16x32_bf16 v[60:63], v[184:187], v[164:167], v[60:63]
	v_mfma_f32_16x16x32_bf16 v[56:59], v[184:187], v[172:175], v[56:59]
	v_mfma_f32_16x16x32_bf16 v[52:55], v[194:197], v[164:167], v[52:55]
	v_mfma_f32_16x16x32_bf16 v[48:51], v[194:197], v[172:175], v[48:51]
	v_mfma_f32_16x16x32_bf16 v[44:47], v[206:209], v[164:167], v[44:47]
	v_mfma_f32_16x16x32_bf16 v[40:43], v[206:209], v[172:175], v[40:43]
	v_mfma_f32_16x16x32_bf16 v[36:39], v[216:219], v[164:167], v[36:39]
	v_mfma_f32_16x16x32_bf16 v[32:35], v[216:219], v[172:175], v[32:35]
	v_mfma_f32_16x16x32_bf16 v[60:63], v[190:193], v[168:171], v[60:63]
	v_mfma_f32_16x16x32_bf16 v[56:59], v[190:193], v[176:179], v[56:59]
	v_mfma_f32_16x16x32_bf16 v[52:55], v[198:201], v[168:171], v[52:55]
	v_mfma_f32_16x16x32_bf16 v[48:51], v[198:201], v[176:179], v[48:51]
	v_mfma_f32_16x16x32_bf16 v[44:47], v[212:215], v[168:171], v[44:47]
	v_mfma_f32_16x16x32_bf16 v[40:43], v[212:215], v[176:179], v[40:43]
	v_mfma_f32_16x16x32_bf16 v[36:39], v[220:223], v[168:171], v[36:39]
	v_mfma_f32_16x16x32_bf16 v[32:35], v[220:223], v[176:179], v[32:35]
	s_barrier
	v_lshl_add_u64 v[252:253], v[140:141], 0, s[6:7]
	s_add_i32 m0, s101, 0x13f00
	global_load_lds_dwordx4 v[252:253], off offset:256
	s_add_i32 m0, m0, 0x2000
	v_lshl_add_u64 v[188:189], v[138:139], 0, s[6:7]
	global_load_lds_dwordx4 v[188:189], off offset:256
	s_waitcnt vmcnt(6)
	s_barrier
	v_mfma_f32_16x16x32_bf16 v[28:31], v[184:187], v[224:227], v[28:31]
	v_mfma_f32_16x16x32_bf16 v[24:27], v[184:187], v[232:235], v[24:27]
	v_mfma_f32_16x16x32_bf16 v[20:23], v[194:197], v[224:227], v[20:23]
	v_mfma_f32_16x16x32_bf16 v[16:19], v[194:197], v[232:235], v[16:19]
	v_mfma_f32_16x16x32_bf16 v[12:15], v[206:209], v[224:227], v[12:15]
	v_mfma_f32_16x16x32_bf16 v[8:11], v[206:209], v[232:235], v[8:11]
	v_mfma_f32_16x16x32_bf16 v[4:7], v[216:219], v[224:227], v[4:7]
	v_mfma_f32_16x16x32_bf16 v[0:3], v[216:219], v[232:235], v[0:3]
	v_mfma_f32_16x16x32_bf16 v[28:31], v[190:193], v[228:231], v[28:31]
	v_mfma_f32_16x16x32_bf16 v[24:27], v[190:193], v[236:239], v[24:27]
	v_mfma_f32_16x16x32_bf16 v[20:23], v[198:201], v[228:231], v[20:23]
	v_mfma_f32_16x16x32_bf16 v[16:19], v[198:201], v[236:239], v[16:19]
	v_mfma_f32_16x16x32_bf16 v[12:15], v[212:215], v[228:231], v[12:15]
	v_mfma_f32_16x16x32_bf16 v[8:11], v[212:215], v[236:239], v[8:11]
	v_mfma_f32_16x16x32_bf16 v[4:7], v[220:223], v[228:231], v[4:7]
	v_mfma_f32_16x16x32_bf16 v[0:3], v[220:223], v[236:239], v[0:3]
	s_barrier
	ds_read_b128 v[164:167], v155
	ds_read_b128 v[168:171], v155 offset:1024
	ds_read_b128 v[172:175], v155 offset:2048
	ds_read_b128 v[176:179], v155 offset:3072
	s_add_i32 m0, s100, 0x3f00
	ds_read_b128 v[184:187], v152 offset:32768
	ds_read_b128 v[190:193], v152 offset:33792
	ds_read_b128 v[194:197], v151 offset:32768
	ds_read_b128 v[198:201], v151 offset:33792
	ds_read_b128 v[206:209], v150 offset:32768
	ds_read_b128 v[212:215], v150 offset:33792
	ds_read_b128 v[216:219], v149 offset:32768
	global_load_lds_dwordx4 v[240:241], off offset:256
	s_add_i32 m0, s100, 0x5f00
	ds_read_b128 v[220:223], v149 offset:33792
	global_load_lds_dwordx4 v[242:243], off offset:256
	s_waitcnt lgkmcnt(8)
	s_barrier
	s_waitcnt lgkmcnt(0)
	v_mfma_f32_16x16x32_bf16 v[124:127], v[184:187], v[164:167], v[124:127]
	v_mfma_f32_16x16x32_bf16 v[120:123], v[184:187], v[172:175], v[120:123]
	v_mfma_f32_16x16x32_bf16 v[116:119], v[194:197], v[164:167], v[116:119]
	v_mfma_f32_16x16x32_bf16 v[112:115], v[194:197], v[172:175], v[112:115]
	v_mfma_f32_16x16x32_bf16 v[108:111], v[206:209], v[164:167], v[108:111]
	v_mfma_f32_16x16x32_bf16 v[104:107], v[206:209], v[172:175], v[104:107]
	v_mfma_f32_16x16x32_bf16 v[100:103], v[216:219], v[164:167], v[100:103]
	v_mfma_f32_16x16x32_bf16 v[96:99], v[216:219], v[172:175], v[96:99]
	v_mfma_f32_16x16x32_bf16 v[124:127], v[190:193], v[168:171], v[124:127]
	v_mfma_f32_16x16x32_bf16 v[120:123], v[190:193], v[176:179], v[120:123]
	v_mfma_f32_16x16x32_bf16 v[116:119], v[198:201], v[168:171], v[116:119]
	v_mfma_f32_16x16x32_bf16 v[112:115], v[198:201], v[176:179], v[112:115]
	v_mfma_f32_16x16x32_bf16 v[108:111], v[212:215], v[168:171], v[108:111]
	v_mfma_f32_16x16x32_bf16 v[104:107], v[212:215], v[176:179], v[104:107]
	v_mfma_f32_16x16x32_bf16 v[100:103], v[220:223], v[168:171], v[100:103]
	v_mfma_f32_16x16x32_bf16 v[96:99], v[220:223], v[176:179], v[96:99]
	s_barrier
	s_add_i32 m0, s101, 0x17e80
	ds_read_b128 v[224:227], v153
	ds_read_b128 v[228:231], v153 offset:1024
	ds_read_b128 v[232:235], v153 offset:2048
	global_load_lds_dwordx4 v[244:245], off offset:384
	s_add_i32 m0, m0, 0x2000
	ds_read_b128 v[236:239], v153 offset:3072
	global_load_lds_dwordx4 v[246:247], off offset:384
	s_barrier
	s_waitcnt lgkmcnt(0)
	v_mfma_f32_16x16x32_bf16 v[92:95], v[184:187], v[224:227], v[92:95]
	v_mfma_f32_16x16x32_bf16 v[88:91], v[184:187], v[232:235], v[88:91]
	v_mfma_f32_16x16x32_bf16 v[84:87], v[194:197], v[224:227], v[84:87]
	v_mfma_f32_16x16x32_bf16 v[80:83], v[194:197], v[232:235], v[80:83]
	v_mfma_f32_16x16x32_bf16 v[76:79], v[206:209], v[224:227], v[76:79]
	v_mfma_f32_16x16x32_bf16 v[72:75], v[206:209], v[232:235], v[72:75]
	v_mfma_f32_16x16x32_bf16 v[68:71], v[216:219], v[224:227], v[68:71]
	v_mfma_f32_16x16x32_bf16 v[64:67], v[216:219], v[232:235], v[64:67]
	v_mfma_f32_16x16x32_bf16 v[92:95], v[190:193], v[228:231], v[92:95]
	v_mfma_f32_16x16x32_bf16 v[88:91], v[190:193], v[236:239], v[88:91]
	v_mfma_f32_16x16x32_bf16 v[84:87], v[198:201], v[228:231], v[84:87]
	v_mfma_f32_16x16x32_bf16 v[80:83], v[198:201], v[236:239], v[80:83]
	v_mfma_f32_16x16x32_bf16 v[76:79], v[212:215], v[228:231], v[76:79]
	v_mfma_f32_16x16x32_bf16 v[72:75], v[212:215], v[236:239], v[72:75]
	v_mfma_f32_16x16x32_bf16 v[68:71], v[220:223], v[228:231], v[68:71]
	v_mfma_f32_16x16x32_bf16 v[64:67], v[220:223], v[236:239], v[64:67]
	s_add_i32 m0, s100, 0x7e80
	s_barrier
	ds_read_b128 v[184:187], v152 offset:49152
	ds_read_b128 v[190:193], v152 offset:50176
	ds_read_b128 v[194:197], v151 offset:49152
	ds_read_b128 v[198:201], v151 offset:50176
	ds_read_b128 v[206:209], v150 offset:49152
	ds_read_b128 v[212:215], v150 offset:50176
	ds_read_b128 v[216:219], v149 offset:49152
	global_load_lds_dwordx4 v[248:249], off offset:384
	s_add_i32 m0, s100, 0x9e80
	ds_read_b128 v[220:223], v149 offset:50176
	global_load_lds_dwordx4 v[250:251], off offset:384
	s_barrier
	s_waitcnt lgkmcnt(0)
	v_mfma_f32_16x16x32_bf16 v[60:63], v[184:187], v[164:167], v[60:63]
	v_mfma_f32_16x16x32_bf16 v[56:59], v[184:187], v[172:175], v[56:59]
	v_mfma_f32_16x16x32_bf16 v[52:55], v[194:197], v[164:167], v[52:55]
	v_mfma_f32_16x16x32_bf16 v[48:51], v[194:197], v[172:175], v[48:51]
	v_mfma_f32_16x16x32_bf16 v[44:47], v[206:209], v[164:167], v[44:47]
	v_mfma_f32_16x16x32_bf16 v[40:43], v[206:209], v[172:175], v[40:43]
	v_mfma_f32_16x16x32_bf16 v[36:39], v[216:219], v[164:167], v[36:39]
	v_mfma_f32_16x16x32_bf16 v[32:35], v[216:219], v[172:175], v[32:35]
	v_mfma_f32_16x16x32_bf16 v[60:63], v[190:193], v[168:171], v[60:63]
	v_mfma_f32_16x16x32_bf16 v[56:59], v[190:193], v[176:179], v[56:59]
	v_mfma_f32_16x16x32_bf16 v[52:55], v[198:201], v[168:171], v[52:55]
	v_mfma_f32_16x16x32_bf16 v[48:51], v[198:201], v[176:179], v[48:51]
	v_mfma_f32_16x16x32_bf16 v[44:47], v[212:215], v[168:171], v[44:47]
	v_mfma_f32_16x16x32_bf16 v[40:43], v[212:215], v[176:179], v[40:43]
	v_mfma_f32_16x16x32_bf16 v[36:39], v[220:223], v[168:171], v[36:39]
	v_mfma_f32_16x16x32_bf16 v[32:35], v[220:223], v[176:179], v[32:35]
	s_barrier
	s_add_i32 m0, s101, 0x1be80
	s_nop 0
	global_load_lds_dwordx4 v[252:253], off offset:384
	s_add_i32 m0, m0, 0x2000
	s_nop 0
	global_load_lds_dwordx4 v[188:189], off offset:384
	s_waitcnt vmcnt(6)
	s_barrier
	v_mfma_f32_16x16x32_bf16 v[28:31], v[184:187], v[224:227], v[28:31]
	v_mfma_f32_16x16x32_bf16 v[24:27], v[184:187], v[232:235], v[24:27]
	v_mfma_f32_16x16x32_bf16 v[20:23], v[194:197], v[224:227], v[20:23]
	v_mfma_f32_16x16x32_bf16 v[16:19], v[194:197], v[232:235], v[16:19]
	v_mfma_f32_16x16x32_bf16 v[12:15], v[206:209], v[224:227], v[12:15]
	v_mfma_f32_16x16x32_bf16 v[8:11], v[206:209], v[232:235], v[8:11]
	v_mfma_f32_16x16x32_bf16 v[4:7], v[216:219], v[224:227], v[4:7]
	v_mfma_f32_16x16x32_bf16 v[0:3], v[216:219], v[232:235], v[0:3]
	v_mfma_f32_16x16x32_bf16 v[28:31], v[190:193], v[228:231], v[28:31]
	v_mfma_f32_16x16x32_bf16 v[24:27], v[190:193], v[236:239], v[24:27]
	v_mfma_f32_16x16x32_bf16 v[20:23], v[198:201], v[228:231], v[20:23]
	v_mfma_f32_16x16x32_bf16 v[16:19], v[198:201], v[236:239], v[16:19]
	v_mfma_f32_16x16x32_bf16 v[12:15], v[212:215], v[228:231], v[12:15]
	v_mfma_f32_16x16x32_bf16 v[8:11], v[212:215], v[236:239], v[8:11]
	v_mfma_f32_16x16x32_bf16 v[4:7], v[220:223], v[228:231], v[4:7]
	v_mfma_f32_16x16x32_bf16 v[0:3], v[220:223], v[236:239], v[0:3]
	s_add_u32 s6, s6, 0x100
	s_addc_u32 s7, s7, 0
	s_cmp_lt_u32 s11, s10
	s_barrier
	s_cbranch_scc1 .LBB0_219
	v_add_u32_e32 v161, 0xc000, v148
	v_add_u32_e32 v162, 0xe000, v148
	s_or_b32 s6, s60, 0x80
	s_mul_hi_u32 s7, s6, s15
	s_mul_i32 s10, s61, s15
	s_add_i32 s7, s7, s10
	s_mul_i32 s6, s6, s15
	s_lshl_b64 s[6:7], s[6:7], 1
	s_add_u32 s6, s4, s6
	s_addc_u32 s7, s5, s7
	s_add_i32 s36, s12, -1
	s_lshl_b64 s[4:5], s[36:37], 7
	s_add_u32 s4, s6, s4
	s_addc_u32 s5, s7, s5
	v_readfirstlane_b32 s6, v161
	v_lshl_add_u64 v[156:157], v[180:181], 1, s[4:5]
	s_mov_b32 m0, s6
	v_lshl_add_u64 v[128:129], v[128:129], 1, s[4:5]
	v_readfirstlane_b32 s4, v162
	ds_read_b128 v[130:133], v160
	ds_read_b128 v[134:137], v160 offset:1024
	ds_read_b128 v[138:141], v160 offset:2048
	ds_read_b128 v[142:145], v160 offset:3072
	ds_read_b128 v[164:167], v152
	ds_read_b128 v[168:171], v152 offset:1024
	ds_read_b128 v[172:175], v151
	ds_read_b128 v[176:179], v151 offset:1024
	ds_read_b128 v[184:187], v150
	ds_read_b128 v[190:193], v150 offset:1024
	ds_read_b128 v[194:197], v149
	ds_read_b128 v[198:201], v149 offset:1024
	global_load_lds_dwordx4 v[156:157], off
	s_mov_b32 m0, s4
	s_nop 0
	global_load_lds_dwordx4 v[128:129], off
	s_barrier
	s_waitcnt lgkmcnt(0)
	s_setprio 1
	s_waitcnt lgkmcnt(0)
	v_mfma_f32_16x16x32_bf16 v[124:127], v[164:167], v[130:133], v[124:127]
	v_mfma_f32_16x16x32_bf16 v[116:119], v[172:175], v[130:133], v[116:119]
	v_mfma_f32_16x16x32_bf16 v[108:111], v[184:187], v[130:133], v[108:111]
	v_mfma_f32_16x16x32_bf16 v[100:103], v[194:197], v[130:133], v[100:103]
	v_mfma_f32_16x16x32_bf16 v[124:127], v[168:171], v[134:137], v[124:127]
	v_mfma_f32_16x16x32_bf16 v[120:123], v[164:167], v[138:141], v[120:123]
	v_mfma_f32_16x16x32_bf16 v[116:119], v[176:179], v[134:137], v[116:119]
	v_mfma_f32_16x16x32_bf16 v[112:115], v[172:175], v[138:141], v[112:115]
	v_mfma_f32_16x16x32_bf16 v[108:111], v[190:193], v[134:137], v[108:111]
	v_mfma_f32_16x16x32_bf16 v[104:107], v[184:187], v[138:141], v[104:107]
	v_mfma_f32_16x16x32_bf16 v[100:103], v[198:201], v[134:137], v[100:103]
	v_mfma_f32_16x16x32_bf16 v[96:99], v[194:197], v[138:141], v[96:99]
	v_mfma_f32_16x16x32_bf16 v[160:163], v[168:171], v[142:145], v[120:123]
	v_mfma_f32_16x16x32_bf16 v[206:209], v[176:179], v[142:145], v[112:115]
	v_mfma_f32_16x16x32_bf16 v[212:215], v[190:193], v[142:145], v[104:107]
	v_mfma_f32_16x16x32_bf16 v[216:219], v[198:201], v[142:145], v[96:99]
	s_setprio 0
	s_barrier
	s_nop 1
	ds_read_b128 v[96:99], v159
	ds_read_b128 v[104:107], v159 offset:1024
	ds_read_b128 v[112:115], v159 offset:2048
	ds_read_b128 v[120:123], v159 offset:3072
	s_barrier
	s_waitcnt lgkmcnt(0)
	s_setprio 1
	s_waitcnt lgkmcnt(0)
	v_mfma_f32_16x16x32_bf16 v[92:95], v[164:167], v[96:99], v[92:95]
	v_mfma_f32_16x16x32_bf16 v[84:87], v[172:175], v[96:99], v[84:87]
	v_mfma_f32_16x16x32_bf16 v[76:79], v[184:187], v[96:99], v[76:79]
	v_mfma_f32_16x16x32_bf16 v[68:71], v[194:197], v[96:99], v[68:71]
	v_mfma_f32_16x16x32_bf16 v[92:95], v[168:171], v[104:107], v[92:95]
	v_mfma_f32_16x16x32_bf16 v[88:91], v[164:167], v[112:115], v[88:91]
	v_mfma_f32_16x16x32_bf16 v[84:87], v[176:179], v[104:107], v[84:87]
	v_mfma_f32_16x16x32_bf16 v[80:83], v[172:175], v[112:115], v[80:83]
	v_mfma_f32_16x16x32_bf16 v[76:79], v[190:193], v[104:107], v[76:79]
	v_mfma_f32_16x16x32_bf16 v[72:75], v[184:187], v[112:115], v[72:75]
	v_mfma_f32_16x16x32_bf16 v[68:71], v[198:201], v[104:107], v[68:71]
	v_mfma_f32_16x16x32_bf16 v[64:67], v[194:197], v[112:115], v[64:67]
	v_mfma_f32_16x16x32_bf16 v[156:159], v[168:171], v[120:123], v[88:91]
	v_mfma_f32_16x16x32_bf16 v[164:167], v[176:179], v[120:123], v[80:83]
	v_mfma_f32_16x16x32_bf16 v[168:171], v[190:193], v[120:123], v[72:75]
	v_mfma_f32_16x16x32_bf16 v[172:175], v[198:201], v[120:123], v[64:67]
	s_setprio 0
	s_barrier
	s_nop 1
	ds_read_b128 v[64:67], v152 offset:16384
	ds_read_b128 v[72:75], v152 offset:17408
	ds_read_b128 v[80:83], v151 offset:16384
	ds_read_b128 v[88:91], v151 offset:17408
	ds_read_b128 v[176:179], v150 offset:16384
	ds_read_b128 v[184:187], v150 offset:17408
	ds_read_b128 v[190:193], v149 offset:16384
	ds_read_b128 v[194:197], v149 offset:17408
	s_waitcnt vmcnt(4)
	s_barrier
	s_waitcnt lgkmcnt(0)
	s_setprio 1
	s_waitcnt lgkmcnt(0)
	v_mfma_f32_16x16x32_bf16 v[60:63], v[64:67], v[130:133], v[60:63]
	v_mfma_f32_16x16x32_bf16 v[52:55], v[80:83], v[130:133], v[52:55]
	v_mfma_f32_16x16x32_bf16 v[44:47], v[176:179], v[130:133], v[44:47]
	v_mfma_f32_16x16x32_bf16 v[36:39], v[190:193], v[130:133], v[36:39]
	v_mfma_f32_16x16x32_bf16 v[60:63], v[72:75], v[134:137], v[60:63]
	v_mfma_f32_16x16x32_bf16 v[56:59], v[64:67], v[138:141], v[56:59]
	v_mfma_f32_16x16x32_bf16 v[52:55], v[88:91], v[134:137], v[52:55]
	v_mfma_f32_16x16x32_bf16 v[48:51], v[80:83], v[138:141], v[48:51]
	v_mfma_f32_16x16x32_bf16 v[44:47], v[184:187], v[134:137], v[44:47]
	v_mfma_f32_16x16x32_bf16 v[40:43], v[176:179], v[138:141], v[40:43]
	v_mfma_f32_16x16x32_bf16 v[36:39], v[194:197], v[134:137], v[36:39]
	v_mfma_f32_16x16x32_bf16 v[32:35], v[190:193], v[138:141], v[32:35]
	v_mfma_f32_16x16x32_bf16 v[198:201], v[72:75], v[142:145], v[56:59]
	v_mfma_f32_16x16x32_bf16 v[220:223], v[88:91], v[142:145], v[48:51]
	v_mfma_f32_16x16x32_bf16 v[224:227], v[184:187], v[142:145], v[40:43]
	v_mfma_f32_16x16x32_bf16 v[128:131], v[194:197], v[142:145], v[32:35]
	s_setprio 0
	s_setprio 1
	v_mfma_f32_16x16x32_bf16 v[28:31], v[64:67], v[96:99], v[28:31]
	v_mfma_f32_16x16x32_bf16 v[20:23], v[80:83], v[96:99], v[20:23]
	v_mfma_f32_16x16x32_bf16 v[12:15], v[176:179], v[96:99], v[12:15]
	v_mfma_f32_16x16x32_bf16 v[4:7], v[190:193], v[96:99], v[4:7]
	v_mfma_f32_16x16x32_bf16 v[28:31], v[72:75], v[104:107], v[28:31]
	v_mfma_f32_16x16x32_bf16 v[24:27], v[64:67], v[112:115], v[24:27]
	v_mfma_f32_16x16x32_bf16 v[20:23], v[88:91], v[104:107], v[20:23]
	v_mfma_f32_16x16x32_bf16 v[16:19], v[80:83], v[112:115], v[16:19]
	v_mfma_f32_16x16x32_bf16 v[12:15], v[184:187], v[104:107], v[12:15]
	v_mfma_f32_16x16x32_bf16 v[8:11], v[176:179], v[112:115], v[8:11]
	v_mfma_f32_16x16x32_bf16 v[4:7], v[194:197], v[104:107], v[4:7]
	v_mfma_f32_16x16x32_bf16 v[0:3], v[190:193], v[112:115], v[0:3]
	v_mfma_f32_16x16x32_bf16 v[132:135], v[72:75], v[120:123], v[24:27]
	v_mfma_f32_16x16x32_bf16 v[136:139], v[88:91], v[120:123], v[16:19]
	v_mfma_f32_16x16x32_bf16 v[140:143], v[184:187], v[120:123], v[8:11]
	v_mfma_f32_16x16x32_bf16 v[176:179], v[194:197], v[120:123], v[0:3]
	s_setprio 0
	s_barrier
	s_nop 1
	ds_read_b128 v[0:3], v155
	ds_read_b128 v[8:11], v155 offset:1024
	ds_read_b128 v[16:19], v155 offset:2048
	ds_read_b128 v[24:27], v155 offset:3072
	ds_read_b128 v[32:35], v152 offset:32768
	ds_read_b128 v[40:43], v152 offset:33792
	ds_read_b128 v[48:51], v151 offset:32768
	ds_read_b128 v[56:59], v151 offset:33792
	ds_read_b128 v[64:67], v150 offset:32768
	ds_read_b128 v[184:187], v150 offset:33792
	ds_read_b128 v[190:193], v149 offset:32768
	ds_read_b128 v[194:197], v149 offset:33792
	s_waitcnt vmcnt(2)
	s_barrier
	s_waitcnt lgkmcnt(0)
	s_setprio 1
	s_waitcnt lgkmcnt(0)
	v_mfma_f32_16x16x32_bf16 v[72:75], v[32:35], v[0:3], v[124:127]
	v_mfma_f32_16x16x32_bf16 v[120:123], v[40:43], v[8:11], v[72:75]
	v_mfma_f32_16x16x32_bf16 v[72:75], v[32:35], v[16:19], v[160:163]
	v_mfma_f32_16x16x32_bf16 v[124:127], v[40:43], v[24:27], v[72:75]
	v_mfma_f32_16x16x32_bf16 v[72:75], v[48:51], v[0:3], v[116:119]
	v_mfma_f32_16x16x32_bf16 v[112:115], v[56:59], v[8:11], v[72:75]
	v_mfma_f32_16x16x32_bf16 v[72:75], v[48:51], v[16:19], v[206:209]
	v_mfma_f32_16x16x32_bf16 v[116:119], v[56:59], v[24:27], v[72:75]
	v_mfma_f32_16x16x32_bf16 v[72:75], v[64:67], v[0:3], v[108:111]
	v_mfma_f32_16x16x32_bf16 v[104:107], v[184:187], v[8:11], v[72:75]
	v_mfma_f32_16x16x32_bf16 v[72:75], v[64:67], v[16:19], v[212:215]
	v_mfma_f32_16x16x32_bf16 v[108:111], v[184:187], v[24:27], v[72:75]
	v_mfma_f32_16x16x32_bf16 v[72:75], v[190:193], v[0:3], v[100:103]
	v_mfma_f32_16x16x32_bf16 v[96:99], v[194:197], v[8:11], v[72:75]
	v_mfma_f32_16x16x32_bf16 v[72:75], v[190:193], v[16:19], v[216:219]
	v_mfma_f32_16x16x32_bf16 v[100:103], v[194:197], v[24:27], v[72:75]
	s_setprio 0
	s_barrier
	ds_read_b128 v[160:163], v153
	ds_read_b128 v[206:209], v153 offset:1024
	ds_read_b128 v[212:215], v153 offset:2048
	ds_read_b128 v[216:219], v153 offset:3072
	s_waitcnt vmcnt(0)
	s_barrier
	s_waitcnt lgkmcnt(0)
	s_setprio 1
	s_waitcnt lgkmcnt(0)
	v_mfma_f32_16x16x32_bf16 v[72:75], v[32:35], v[160:163], v[92:95]
	v_mfma_f32_16x16x32_bf16 v[32:35], v[32:35], v[212:215], v[156:159]
	v_mfma_f32_16x16x32_bf16 v[92:95], v[40:43], v[216:219], v[32:35]
	v_mfma_f32_16x16x32_bf16 v[32:35], v[48:51], v[160:163], v[84:87]
	v_mfma_f32_16x16x32_bf16 v[80:83], v[56:59], v[206:209], v[32:35]
	v_mfma_f32_16x16x32_bf16 v[32:35], v[48:51], v[212:215], v[164:167]
	v_mfma_f32_16x16x32_bf16 v[84:87], v[56:59], v[216:219], v[32:35]
	v_mfma_f32_16x16x32_bf16 v[32:35], v[64:67], v[160:163], v[76:79]
	v_mfma_f32_16x16x32_bf16 v[88:91], v[40:43], v[206:209], v[72:75]
	v_mfma_f32_16x16x32_bf16 v[72:75], v[184:187], v[206:209], v[32:35]
	v_mfma_f32_16x16x32_bf16 v[32:35], v[64:67], v[212:215], v[168:171]
	v_mfma_f32_16x16x32_bf16 v[76:79], v[184:187], v[216:219], v[32:35]
	v_mfma_f32_16x16x32_bf16 v[32:35], v[190:193], v[160:163], v[68:71]
	v_mfma_f32_16x16x32_bf16 v[64:67], v[194:197], v[206:209], v[32:35]
	v_mfma_f32_16x16x32_bf16 v[32:35], v[190:193], v[212:215], v[172:175]
	v_mfma_f32_16x16x32_bf16 v[68:71], v[194:197], v[216:219], v[32:35]
	s_setprio 0
	s_barrier
	ds_read_b128 v[154:157], v152 offset:49152
	ds_read_b128 v[164:167], v152 offset:50176
	ds_read_b128 v[168:171], v151 offset:49152
	ds_read_b128 v[172:175], v151 offset:50176
	ds_read_b128 v[184:187], v150 offset:49152
	ds_read_b128 v[150:153], v150 offset:50176
	ds_read_b128 v[190:193], v149 offset:49152
	ds_read_b128 v[194:197], v149 offset:50176
	s_barrier
	s_waitcnt lgkmcnt(0)
	s_setprio 1
	s_waitcnt lgkmcnt(0)
	v_mfma_f32_16x16x32_bf16 v[32:35], v[154:157], v[0:3], v[60:63]
	v_mfma_f32_16x16x32_bf16 v[56:59], v[164:167], v[8:11], v[32:35]
	v_mfma_f32_16x16x32_bf16 v[32:35], v[154:157], v[16:19], v[198:201]
	v_mfma_f32_16x16x32_bf16 v[60:63], v[164:167], v[24:27], v[32:35]
	v_mfma_f32_16x16x32_bf16 v[32:35], v[168:171], v[0:3], v[52:55]
	v_mfma_f32_16x16x32_bf16 v[48:51], v[172:175], v[8:11], v[32:35]
	v_mfma_f32_16x16x32_bf16 v[32:35], v[168:171], v[16:19], v[220:223]
	v_mfma_f32_16x16x32_bf16 v[52:55], v[172:175], v[24:27], v[32:35]
	v_mfma_f32_16x16x32_bf16 v[32:35], v[184:187], v[0:3], v[44:47]
	v_mfma_f32_16x16x32_bf16 v[40:43], v[150:153], v[8:11], v[32:35]
	v_mfma_f32_16x16x32_bf16 v[32:35], v[184:187], v[16:19], v[224:227]
	v_mfma_f32_16x16x32_bf16 v[0:3], v[190:193], v[0:3], v[36:39]
	v_mfma_f32_16x16x32_bf16 v[44:47], v[150:153], v[24:27], v[32:35]
	v_mfma_f32_16x16x32_bf16 v[32:35], v[194:197], v[8:11], v[0:3]
	v_mfma_f32_16x16x32_bf16 v[0:3], v[190:193], v[16:19], v[128:131]
	v_mfma_f32_16x16x32_bf16 v[36:39], v[194:197], v[24:27], v[0:3]
	s_setprio 0
	s_setprio 1
	v_mfma_f32_16x16x32_bf16 v[0:3], v[154:157], v[160:163], v[28:31]
	v_mfma_f32_16x16x32_bf16 v[24:27], v[164:167], v[206:209], v[0:3]
	v_mfma_f32_16x16x32_bf16 v[0:3], v[154:157], v[212:215], v[132:135]
	v_mfma_f32_16x16x32_bf16 v[28:31], v[164:167], v[216:219], v[0:3]
	v_mfma_f32_16x16x32_bf16 v[0:3], v[168:171], v[160:163], v[20:23]
	v_mfma_f32_16x16x32_bf16 v[16:19], v[172:175], v[206:209], v[0:3]
	v_mfma_f32_16x16x32_bf16 v[0:3], v[168:171], v[212:215], v[136:139]
	v_mfma_f32_16x16x32_bf16 v[20:23], v[172:175], v[216:219], v[0:3]
	v_mfma_f32_16x16x32_bf16 v[0:3], v[184:187], v[160:163], v[12:15]
	v_mfma_f32_16x16x32_bf16 v[8:11], v[150:153], v[206:209], v[0:3]
	v_mfma_f32_16x16x32_bf16 v[0:3], v[184:187], v[212:215], v[140:143]
	v_mfma_f32_16x16x32_bf16 v[12:15], v[150:153], v[216:219], v[0:3]
	v_mfma_f32_16x16x32_bf16 v[0:3], v[190:193], v[160:163], v[4:7]
	v_mfma_f32_16x16x32_bf16 v[4:7], v[190:193], v[212:215], v[176:179]
	v_mfma_f32_16x16x32_bf16 v[0:3], v[194:197], v[206:209], v[0:3]
	v_mfma_f32_16x16x32_bf16 v[4:7], v[194:197], v[216:219], v[4:7]
	s_setprio 0
	s_movk_i32 s4, 0x100
	v_cmp_gt_u32_e32 vcc, s4, v146
	s_barrier
	s_and_saveexec_b64 s[4:5], vcc
	s_cbranch_execz .LBB0_222
	s_barrier
